# s_setprio 1/0 flips around MLA PV-group and S-burst MFMA regions (plus GEMM K-loop flips)
# speedup vs baseline: 1.0559x; 1.0187x over previous
.LBB0_295:
	v_exp_f32_e32 v82, v82
	v_exp_f32_e32 v83, v83
	v_exp_f32_e32 v84, v84
	v_exp_f32_e32 v85, v85
	v_exp_f32_e32 v86, v86
	v_exp_f32_e32 v87, v87
	v_exp_f32_e32 v88, v88
	v_exp_f32_e32 v89, v89
	v_cvt_pk_bf16_f32 v82, v82, v83
	v_cvt_pk_bf16_f32 v83, v84, v85
	v_cvt_pk_bf16_f32 v84, v86, v87
	v_cvt_pk_bf16_f32 v85, v88, v89
	s_add_i32 s5, s0, 1
	s_cmp_lg_u32 s0, 2
	s_waitcnt lgkmcnt(0)
	s_setprio 1
	v_mfma_f32_16x16x32_bf16 v[26:29], v[98:101], v[82:85], v[26:29]
	v_exp_f32_e32 v74, v74
	v_exp_f32_e32 v75, v75
	v_mfma_f32_16x16x32_bf16 v[2:5], v[94:97], v[82:85], v[2:5]
	v_exp_f32_e32 v76, v76
	v_exp_f32_e32 v77, v77
	v_mfma_f32_16x16x32_bf16 v[10:13], v[110:113], v[82:85], v[10:13]
	v_exp_f32_e32 v78, v78
	v_exp_f32_e32 v79, v79
	v_mfma_f32_16x16x32_bf16 v[22:25], v[114:117], v[82:85], v[22:25]
	v_exp_f32_e32 v80, v80
	v_exp_f32_e32 v81, v81
	v_cvt_pk_bf16_f32 v74, v74, v75
	v_cvt_pk_bf16_f32 v75, v76, v77
	v_mfma_f32_16x16x32_bf16 v[38:41], v[236:239], v[82:85], v[38:41]
	v_cvt_pk_bf16_f32 v76, v78, v79
	v_cvt_pk_bf16_f32 v77, v80, v81
	s_cselect_b32 s0, s5, 0
	s_add_i32 s5, s4, 1
	v_mfma_f32_16x16x32_bf16 v[30:33], v[98:101], v[74:77], v[30:33]
	v_exp_f32_e32 v86, v118
	v_exp_f32_e32 v87, v119
	v_mfma_f32_16x16x32_bf16 v[6:9], v[94:97], v[74:77], v[6:9]
	v_exp_f32_e32 v88, v120
	v_exp_f32_e32 v89, v121
	v_mfma_f32_16x16x32_bf16 v[14:17], v[110:113], v[74:77], v[14:17]
	v_exp_f32_e32 v118, v122
	v_exp_f32_e32 v119, v123
	v_mfma_f32_16x16x32_bf16 v[18:21], v[114:117], v[74:77], v[18:21]
	v_exp_f32_e32 v120, v124
	v_exp_f32_e32 v121, v125
	v_cvt_pk_bf16_f32 v86, v86, v87
	v_cvt_pk_bf16_f32 v87, v88, v89
	v_mfma_f32_16x16x32_bf16 v[34:37], v[236:239], v[74:77], v[34:37]
	v_cvt_pk_bf16_f32 v88, v118, v119
	v_cvt_pk_bf16_f32 v89, v120, v121
	s_cmp_lg_u32 s4, 2
	s_cselect_b32 s4, s5, 0
	v_mfma_f32_16x16x32_bf16 v[26:29], v[90:93], v[86:89], v[26:29]
	v_exp_f32_e32 v66, v66
	v_exp_f32_e32 v67, v67
	v_mfma_f32_16x16x32_bf16 v[2:5], v[106:109], v[86:89], v[2:5]
	v_exp_f32_e32 v68, v68
	v_exp_f32_e32 v69, v69
	v_mfma_f32_16x16x32_bf16 v[10:13], v[102:105], v[86:89], v[10:13]
	v_exp_f32_e32 v70, v70
	v_exp_f32_e32 v71, v71
	v_mfma_f32_16x16x32_bf16 v[22:25], v[126:129], v[86:89], v[22:25]
	v_exp_f32_e32 v72, v72
	v_exp_f32_e32 v73, v73
	v_cvt_pk_bf16_f32 v66, v66, v67
	v_cvt_pk_bf16_f32 v67, v68, v69
	v_mfma_f32_16x16x32_bf16 v[38:41], v[236:239], v[86:89], v[38:41]
	v_cvt_pk_bf16_f32 v68, v70, v71
	v_cvt_pk_bf16_f32 v69, v72, v73
	v_lshl_add_u64 v[136:137], v[136:137], 0, s[24:25]
	v_lshl_add_u64 v[138:139], v[138:139], 0, s[78:79]
	s_cmp_lg_u32 s2, s1
	v_mfma_f32_16x16x32_bf16 v[30:33], v[90:93], v[66:69], v[30:33]
	v_mfma_f32_16x16x32_bf16 v[6:9], v[106:109], v[66:69], v[6:9]
	v_mfma_f32_16x16x32_bf16 v[14:17], v[102:105], v[66:69], v[14:17]
	v_mfma_f32_16x16x32_bf16 v[18:21], v[126:129], v[66:69], v[18:21]
	v_mfma_f32_16x16x32_bf16 v[34:37], v[236:239], v[66:69], v[34:37]
	s_setprio 0
	s_cbranch_scc0 .LBB0_302
.LBB0_296:
	s_waitcnt vmcnt(5) lgkmcnt(0)
	s_barrier
	s_mul_i32 s5, s0, 0x5000
	v_add_u32_e32 v144, s5, v143
	ds_read_b128 v[66:69], v144
	ds_read_b128 v[74:77], v144 offset:4096
	ds_read_b128 v[78:81], v144 offset:8192
	ds_read_b128 v[86:89], v144 offset:1024
	ds_read_b128 v[90:93], v144 offset:5120
	ds_read_b128 v[94:97], v144 offset:9216
	ds_read_b128 v[98:101], v144 offset:2048
	ds_read_b128 v[102:105], v144 offset:6144
	ds_read_b128 v[106:109], v144 offset:10240
	ds_read_b128 v[110:113], v144 offset:3072
	ds_read_b128 v[114:117], v144 offset:7168
	ds_read_b128 v[126:129], v144 offset:11264
	s_add_i32 s1, s1, 1
	s_mul_i32 s5, s4, 0x5000
	s_add_i32 s5, s5, s100
	s_mov_b32 m0, s5
	s_add_i32 s6, s5, 0xfc0
	s_waitcnt lgkmcnt(9)
	s_setprio 1
	v_mfma_f32_16x16x32_bf16 v[82:85], v[66:69], v[46:49], v[228:231]
	v_mfma_f32_16x16x32_bf16 v[66:69], v[66:69], v[62:65], v[232:235]
	v_mfma_f32_16x16x32_bf16 v[66:69], v[74:77], v[58:61], v[66:69]
	global_load_lds_dwordx4 v[136:137], off
	v_mfma_f32_16x16x32_bf16 v[82:85], v[74:77], v[42:45], v[82:85]
	s_mov_b32 m0, s6
	v_mfma_f32_16x16x32_bf16 v[74:77], v[78:81], v[54:57], v[66:69]
	s_add_i32 s6, s5, 0x1f80
	s_waitcnt lgkmcnt(6)
	v_mfma_f32_16x16x32_bf16 v[66:69], v[86:89], v[46:49], v[228:231]
	v_mfma_f32_16x16x32_bf16 v[82:85], v[78:81], v[50:53], v[82:85]
	global_load_lds_dwordx4 v[136:137], off offset:64
	v_mfma_f32_16x16x32_bf16 v[78:81], v[86:89], v[62:65], v[232:235]
	s_mov_b32 m0, s6
	v_mfma_f32_16x16x32_bf16 v[66:69], v[90:93], v[42:45], v[66:69]
	s_add_i32 s6, s5, 0x3000
	v_mfma_f32_16x16x32_bf16 v[78:81], v[90:93], v[58:61], v[78:81]
	global_load_lds_dwordx4 v[136:137], off offset:128
	v_mfma_f32_16x16x32_bf16 v[86:89], v[94:97], v[50:53], v[66:69]
	s_mov_b32 m0, s6
	s_add_i32 s6, s5, 0x3fc0
	s_waitcnt lgkmcnt(3)
	v_mfma_f32_16x16x32_bf16 v[66:69], v[98:101], v[46:49], v[228:231]
	v_mfma_f32_16x16x32_bf16 v[90:93], v[98:101], v[62:65], v[232:235]
	global_load_lds_dwordx4 v[138:139], off
	v_mfma_f32_16x16x32_bf16 v[66:69], v[102:105], v[42:45], v[66:69]
	s_mov_b32 m0, s6
	v_mfma_f32_16x16x32_bf16 v[90:93], v[102:105], v[58:61], v[90:93]
	v_mfma_f32_16x16x32_bf16 v[118:121], v[106:109], v[50:53], v[66:69]
	global_load_lds_dwordx4 v[138:139], off offset:64
	v_mfma_f32_16x16x32_bf16 v[66:69], v[106:109], v[54:57], v[90:93]
	s_waitcnt lgkmcnt(0)
	v_mfma_f32_16x16x32_bf16 v[90:93], v[110:113], v[46:49], v[228:231]
	v_mfma_f32_16x16x32_bf16 v[70:73], v[110:113], v[62:65], v[232:235]
	v_mfma_f32_16x16x32_bf16 v[90:93], v[114:117], v[42:45], v[90:93]
	v_mfma_f32_16x16x32_bf16 v[70:73], v[114:117], v[58:61], v[70:73]
	v_mfma_f32_16x16x32_bf16 v[78:81], v[94:97], v[54:57], v[78:81]
	v_mfma_f32_16x16x32_bf16 v[122:125], v[126:129], v[50:53], v[90:93]
	v_mfma_f32_16x16x32_bf16 v[70:73], v[126:129], v[54:57], v[70:73]
	s_setprio 0
	ds_read_b128 v[98:101], v144 offset:12288
	s_nop 2
	ds_read_b128 v[90:93], v144 offset:16384
	ds_read_b128 v[94:97], v144 offset:13312
	ds_read_b128 v[106:109], v144 offset:17408
	ds_read_b128 v[110:113], v144 offset:14336
	ds_read_b128 v[102:105], v144 offset:18432
	ds_read_b128 v[114:117], v144 offset:15360
	ds_read_b128 v[126:129], v144 offset:19456
	v_max3_f32 v144, v82, v83, v84
	v_max3_f32 v144, v144, v85, v86
	v_max3_f32 v144, v144, v87, v88
	v_max3_f32 v144, v144, v89, v118
	v_max3_f32 v144, v144, v119, v120
	v_max3_f32 v144, v144, v121, v122
	v_max3_f32 v144, v144, v123, v124
	v_max_f32_e32 v144, v144, v125
	v_cmp_lt_f32_e32 vcc, s8, v144
	s_cbranch_vccz .LBB0_300
	v_mov_b32_e32 v145, v144
	s_nop 1
	v_permlane32_swap_b32_e32 v144, v145
	v_max_f32_e32 v145, v145, v145
	v_max_f32_e32 v144, v144, v144
	v_max_f32_e32 v144, v144, v145
	v_mov_b32_e32 v145, v144
	s_nop 1
	v_permlane16_swap_b32_e32 v144, v145
	v_max_f32_e32 v145, v145, v145
	v_max_f32_e32 v144, v144, v144
	v_max_f32_e32 v144, v144, v145
	v_max_f32_e32 v144, v144, v144
	v_max_f32_e32 v145, 0, v144
	v_exp_f32_e64 v144, -v145
	v_add_f32_e32 v134, v134, v145
	v_sub_f32_e32 v82, v82, v145
	v_sub_f32_e32 v83, v83, v145
	v_pk_mul_f32 v[40:41], v[40:41], v[144:145] op_sel_hi:[1,0]
	v_pk_mul_f32 v[38:39], v[38:39], v[144:145] op_sel_hi:[1,0]
	v_pk_mul_f32 v[28:29], v[28:29], v[144:145] op_sel_hi:[1,0]
	v_pk_mul_f32 v[26:27], v[26:27], v[144:145] op_sel_hi:[1,0]
	v_sub_f32_e32 v84, v84, v145
	v_sub_f32_e32 v85, v85, v145
	v_pk_mul_f32 v[4:5], v[4:5], v[144:145] op_sel_hi:[1,0]
	v_pk_mul_f32 v[2:3], v[2:3], v[144:145] op_sel_hi:[1,0]
	v_sub_f32_e32 v86, v86, v145
	v_sub_f32_e32 v87, v87, v145
	v_sub_f32_e32 v88, v88, v145
	v_sub_f32_e32 v89, v89, v145
	v_pk_mul_f32 v[12:13], v[12:13], v[144:145] op_sel_hi:[1,0]
	v_pk_mul_f32 v[10:11], v[10:11], v[144:145] op_sel_hi:[1,0]
	v_sub_f32_e32 v118, v118, v145
	v_sub_f32_e32 v119, v119, v145
	v_sub_f32_e32 v120, v120, v145
	v_sub_f32_e32 v121, v121, v145
	v_pk_mul_f32 v[24:25], v[24:25], v[144:145] op_sel_hi:[1,0]
	v_pk_mul_f32 v[22:23], v[22:23], v[144:145] op_sel_hi:[1,0]
	v_sub_f32_e32 v122, v122, v145
	v_sub_f32_e32 v123, v123, v145
	v_sub_f32_e32 v124, v124, v145
	v_sub_f32_e32 v125, v125, v145
	v_xor_b32_e32 v228, 0x80000000, v134
	v_mov_b32_e32 v229, v228
	v_mov_b32_e32 v230, v228
	v_mov_b32_e32 v231, v228
